# attention loop: exp/sum/pack split into four 8-score groups, group g+1 issued between the PV MFMAs of group g; V operand registers recycled
# speedup vs baseline: 1.0430x; 1.0096x over previous
.Lfa_e_sm:
	s_waitcnt lgkmcnt(9)
	ds_read_b64_tr_b16 v[232:233], v200 offset:22720
	ds_read_b64_tr_b16 v[234:235], v200 offset:25280
	ds_read_b64_tr_b16 v[236:237], v200 offset:27648
	ds_read_b64_tr_b16 v[238:239], v200 offset:30208
	ds_read_b64_tr_b16 v[240:241], v200 offset:27712
	ds_read_b64_tr_b16 v[242:243], v200 offset:30272
	v_exp_f32_e32 v96, v96
	v_exp_f32_e32 v97, v97
	v_exp_f32_e32 v98, v98
	v_exp_f32_e32 v99, v99
	v_exp_f32_e32 v100, v100
	v_exp_f32_e32 v101, v101
	v_exp_f32_e32 v102, v102
	v_exp_f32_e32 v103, v103
	v_add_f32_e32 v0, v96, v97
	v_add_f32_e32 v0, v0, v98
	v_add_f32_e32 v0, v0, v99
	v_add_f32_e32 v0, v0, v100
	v_add_f32_e32 v0, v0, v101
	v_add_f32_e32 v0, v0, v102
	v_add_f32_e32 v0, v0, v103
	v_cvt_pk_bf16_f32 v96, v96, v97
	v_cvt_pk_bf16_f32 v97, v98, v99
	v_cvt_pk_bf16_f32 v98, v100, v101
	v_cvt_pk_bf16_f32 v99, v102, v103
	v_add_f32_e32 v183, v183, v0
	s_nop 0
	v_mfma_f32_32x32x16_bf16 v[80:95], v[244:247], v[96:99], v[80:95]
	v_exp_f32_e32 v104, v104
	v_exp_f32_e32 v105, v105
	v_mfma_f32_32x32x16_bf16 v[64:79], v[248:251], v[96:99], v[64:79]
	v_exp_f32_e32 v106, v106
	v_exp_f32_e32 v107, v107
	v_add_f32_e32 v0, v104, v105
	s_waitcnt lgkmcnt(14)
	v_mfma_f32_32x32x16_bf16 v[48:63], v[212:215], v[96:99], v[48:63]
	v_exp_f32_e32 v108, v108
	v_exp_f32_e32 v109, v109
	v_add_f32_e32 v0, v0, v106
	v_add_f32_e32 v0, v0, v107
	s_waitcnt lgkmcnt(12)
	v_mfma_f32_32x32x16_bf16 v[32:47], v[216:219], v[96:99], v[32:47]
	ds_read_b64_tr_b16 v[244:245], v200 offset:27776
	ds_read_b64_tr_b16 v[246:247], v200 offset:30336
	v_exp_f32_e32 v110, v110
	v_exp_f32_e32 v111, v111
	v_add_f32_e32 v0, v0, v108
	v_add_f32_e32 v0, v0, v109
	v_add_f32_e32 v0, v0, v110
	v_add_f32_e32 v0, v0, v111
	v_cvt_pk_bf16_f32 v104, v104, v105
	v_cvt_pk_bf16_f32 v105, v106, v107
	v_cvt_pk_bf16_f32 v106, v108, v109
	v_cvt_pk_bf16_f32 v107, v110, v111
	v_add_f32_e32 v183, v183, v0
	s_nop 0
	s_waitcnt lgkmcnt(12)
	v_mfma_f32_32x32x16_bf16 v[80:95], v[220:223], v[104:107], v[80:95]
	ds_read_b64_tr_b16 v[248:249], v200 offset:27840
	ds_read_b64_tr_b16 v[250:251], v200 offset:30400
	v_exp_f32_e32 v112, v112
	v_exp_f32_e32 v113, v113
	s_waitcnt lgkmcnt(12)
	v_mfma_f32_32x32x16_bf16 v[64:79], v[224:227], v[104:107], v[64:79]
	ds_read_b64_tr_b16 v[212:213], v200 offset:32768
	ds_read_b64_tr_b16 v[214:215], v200 offset:35328
	v_exp_f32_e32 v114, v114
	v_exp_f32_e32 v115, v115
	v_add_f32_e32 v0, v112, v113
	s_waitcnt lgkmcnt(12)
	v_mfma_f32_32x32x16_bf16 v[48:63], v[228:231], v[104:107], v[48:63]
	ds_read_b64_tr_b16 v[216:217], v200 offset:32832
	ds_read_b64_tr_b16 v[218:219], v200 offset:35392
	v_exp_f32_e32 v116, v116
	v_exp_f32_e32 v117, v117
	v_add_f32_e32 v0, v0, v114
	v_add_f32_e32 v0, v0, v115
	s_waitcnt lgkmcnt(12)
	v_mfma_f32_32x32x16_bf16 v[32:47], v[232:235], v[104:107], v[32:47]
	ds_read_b64_tr_b16 v[220:221], v200 offset:32896
	ds_read_b64_tr_b16 v[222:223], v200 offset:35456
	v_exp_f32_e32 v118, v118
	v_exp_f32_e32 v119, v119
	v_add_f32_e32 v0, v0, v116
	v_add_f32_e32 v0, v0, v117
	v_add_f32_e32 v0, v0, v118
	v_add_f32_e32 v0, v0, v119
	v_cvt_pk_bf16_f32 v112, v112, v113
	v_cvt_pk_bf16_f32 v113, v114, v115
	v_cvt_pk_bf16_f32 v114, v116, v117
	v_cvt_pk_bf16_f32 v115, v118, v119
	v_add_f32_e32 v183, v183, v0
	s_nop 0
	s_waitcnt lgkmcnt(12)
	v_mfma_f32_32x32x16_bf16 v[80:95], v[236:239], v[112:115], v[80:95]
	ds_read_b64_tr_b16 v[224:225], v200 offset:32960
	ds_read_b64_tr_b16 v[226:227], v200 offset:35520
	v_exp_f32_e32 v120, v120
	v_exp_f32_e32 v121, v121
	s_waitcnt lgkmcnt(12)
	v_mfma_f32_32x32x16_bf16 v[64:79], v[240:243], v[112:115], v[64:79]
	v_exp_f32_e32 v122, v122
	v_exp_f32_e32 v123, v123
	v_add_f32_e32 v0, v120, v121
	s_waitcnt lgkmcnt(10)
	v_mfma_f32_32x32x16_bf16 v[48:63], v[244:247], v[112:115], v[48:63]
	v_exp_f32_e32 v124, v124
	v_exp_f32_e32 v125, v125
	v_add_f32_e32 v0, v0, v122
	v_add_f32_e32 v0, v0, v123
	s_waitcnt lgkmcnt(8)
	v_mfma_f32_32x32x16_bf16 v[32:47], v[248:251], v[112:115], v[32:47]
	v_exp_f32_e32 v126, v126
	v_exp_f32_e32 v127, v127
	v_add_f32_e32 v0, v0, v124
	v_add_f32_e32 v0, v0, v125
	v_add_f32_e32 v0, v0, v126
	v_add_f32_e32 v0, v0, v127
	v_cvt_pk_bf16_f32 v120, v120, v121
	v_cvt_pk_bf16_f32 v121, v122, v123
	v_cvt_pk_bf16_f32 v122, v124, v125
	v_cvt_pk_bf16_f32 v123, v126, v127
	v_add_f32_e32 v183, v183, v0
	s_nop 0
	s_waitcnt lgkmcnt(6)
	v_mfma_f32_32x32x16_bf16 v[80:95], v[212:215], v[120:123], v[80:95]
	s_waitcnt lgkmcnt(4)
	v_mfma_f32_32x32x16_bf16 v[64:79], v[216:219], v[120:123], v[64:79]
	s_waitcnt lgkmcnt(2)
	v_mfma_f32_32x32x16_bf16 v[48:63], v[220:223], v[120:123], v[48:63]
	s_waitcnt lgkmcnt(0)
	v_mfma_f32_32x32x16_bf16 v[32:47], v[224:227], v[120:123], v[32:47]
	s_cmp_lg_u32 s73, 0
	s_cbranch_scc1 .Lfa_e_bar
	s_waitcnt vmcnt(6)
	ds_write_b128 v14, v[160:163] offset:37888
	ds_write_b128 v15, v[164:167] offset:55296
	s_waitcnt vmcnt(5)
	ds_write_b128 v202, v[168:171] offset:37888
	s_waitcnt vmcnt(4)
	ds_write_b128 v203, v[172:175] offset:55296

.Lfa_o_sm:
	s_waitcnt lgkmcnt(9)
	ds_read_b64_tr_b16 v[232:233], v200 offset:60608
	ds_read_b64_tr_b16 v[234:235], v200 offset:63168
	ds_read_b64_tr_b16 v[236:237], v209 offset:0
	ds_read_b64_tr_b16 v[238:239], v209 offset:2560
	ds_read_b64_tr_b16 v[240:241], v209 offset:64
	ds_read_b64_tr_b16 v[242:243], v209 offset:2624
	v_exp_f32_e32 v96, v96
	v_exp_f32_e32 v97, v97
	v_exp_f32_e32 v98, v98
	v_exp_f32_e32 v99, v99
	v_exp_f32_e32 v100, v100
	v_exp_f32_e32 v101, v101
	v_exp_f32_e32 v102, v102
	v_exp_f32_e32 v103, v103
	v_add_f32_e32 v0, v96, v97
	v_add_f32_e32 v0, v0, v98
	v_add_f32_e32 v0, v0, v99
	v_add_f32_e32 v0, v0, v100
	v_add_f32_e32 v0, v0, v101
	v_add_f32_e32 v0, v0, v102
	v_add_f32_e32 v0, v0, v103
	v_cvt_pk_bf16_f32 v96, v96, v97
	v_cvt_pk_bf16_f32 v97, v98, v99
	v_cvt_pk_bf16_f32 v98, v100, v101
	v_cvt_pk_bf16_f32 v99, v102, v103
	v_add_f32_e32 v183, v183, v0
	s_nop 0
	v_mfma_f32_32x32x16_bf16 v[80:95], v[244:247], v[96:99], v[80:95]
	v_exp_f32_e32 v104, v104
	v_exp_f32_e32 v105, v105
	v_mfma_f32_32x32x16_bf16 v[64:79], v[248:251], v[96:99], v[64:79]
	v_exp_f32_e32 v106, v106
	v_exp_f32_e32 v107, v107
	v_add_f32_e32 v0, v104, v105
	s_waitcnt lgkmcnt(14)
	v_mfma_f32_32x32x16_bf16 v[48:63], v[212:215], v[96:99], v[48:63]
	v_exp_f32_e32 v108, v108
	v_exp_f32_e32 v109, v109
	v_add_f32_e32 v0, v0, v106
	v_add_f32_e32 v0, v0, v107
	s_waitcnt lgkmcnt(12)
	v_mfma_f32_32x32x16_bf16 v[32:47], v[216:219], v[96:99], v[32:47]
	ds_read_b64_tr_b16 v[244:245], v209 offset:128
	ds_read_b64_tr_b16 v[246:247], v209 offset:2688
	v_exp_f32_e32 v110, v110
	v_exp_f32_e32 v111, v111
	v_add_f32_e32 v0, v0, v108
	v_add_f32_e32 v0, v0, v109
	v_add_f32_e32 v0, v0, v110
	v_add_f32_e32 v0, v0, v111
	v_cvt_pk_bf16_f32 v104, v104, v105
	v_cvt_pk_bf16_f32 v105, v106, v107
	v_cvt_pk_bf16_f32 v106, v108, v109
	v_cvt_pk_bf16_f32 v107, v110, v111
	v_add_f32_e32 v183, v183, v0
	s_nop 0
	s_waitcnt lgkmcnt(12)
	v_mfma_f32_32x32x16_bf16 v[80:95], v[220:223], v[104:107], v[80:95]
	ds_read_b64_tr_b16 v[248:249], v209 offset:192
	ds_read_b64_tr_b16 v[250:251], v209 offset:2752
	v_exp_f32_e32 v112, v112
	v_exp_f32_e32 v113, v113
	s_waitcnt lgkmcnt(12)
	v_mfma_f32_32x32x16_bf16 v[64:79], v[224:227], v[104:107], v[64:79]
	ds_read_b64_tr_b16 v[212:213], v209 offset:5120
	ds_read_b64_tr_b16 v[214:215], v209 offset:7680
	v_exp_f32_e32 v114, v114
	v_exp_f32_e32 v115, v115
	v_add_f32_e32 v0, v112, v113
	s_waitcnt lgkmcnt(12)
	v_mfma_f32_32x32x16_bf16 v[48:63], v[228:231], v[104:107], v[48:63]
	ds_read_b64_tr_b16 v[216:217], v209 offset:5184
	ds_read_b64_tr_b16 v[218:219], v209 offset:7744
	v_exp_f32_e32 v116, v116
	v_exp_f32_e32 v117, v117
	v_add_f32_e32 v0, v0, v114
	v_add_f32_e32 v0, v0, v115
	s_waitcnt lgkmcnt(12)
	v_mfma_f32_32x32x16_bf16 v[32:47], v[232:235], v[104:107], v[32:47]
	ds_read_b64_tr_b16 v[220:221], v209 offset:5248
	ds_read_b64_tr_b16 v[222:223], v209 offset:7808
	v_exp_f32_e32 v118, v118
	v_exp_f32_e32 v119, v119
	v_add_f32_e32 v0, v0, v116
	v_add_f32_e32 v0, v0, v117
	v_add_f32_e32 v0, v0, v118
	v_add_f32_e32 v0, v0, v119
	v_cvt_pk_bf16_f32 v112, v112, v113
	v_cvt_pk_bf16_f32 v113, v114, v115
	v_cvt_pk_bf16_f32 v114, v116, v117
	v_cvt_pk_bf16_f32 v115, v118, v119
	v_add_f32_e32 v183, v183, v0
	s_nop 0
	s_waitcnt lgkmcnt(12)
	v_mfma_f32_32x32x16_bf16 v[80:95], v[236:239], v[112:115], v[80:95]
	ds_read_b64_tr_b16 v[224:225], v209 offset:5312
	ds_read_b64_tr_b16 v[226:227], v209 offset:7872
	v_exp_f32_e32 v120, v120
	v_exp_f32_e32 v121, v121
	s_waitcnt lgkmcnt(12)
	v_mfma_f32_32x32x16_bf16 v[64:79], v[240:243], v[112:115], v[64:79]
	v_exp_f32_e32 v122, v122
	v_exp_f32_e32 v123, v123
	v_add_f32_e32 v0, v120, v121
	s_waitcnt lgkmcnt(10)
	v_mfma_f32_32x32x16_bf16 v[48:63], v[244:247], v[112:115], v[48:63]
	v_exp_f32_e32 v124, v124
	v_exp_f32_e32 v125, v125
	v_add_f32_e32 v0, v0, v122
	v_add_f32_e32 v0, v0, v123
	s_waitcnt lgkmcnt(8)
	v_mfma_f32_32x32x16_bf16 v[32:47], v[248:251], v[112:115], v[32:47]
	v_exp_f32_e32 v126, v126
	v_exp_f32_e32 v127, v127
	v_add_f32_e32 v0, v0, v124
	v_add_f32_e32 v0, v0, v125
	v_add_f32_e32 v0, v0, v126
	v_add_f32_e32 v0, v0, v127
	v_cvt_pk_bf16_f32 v120, v120, v121
	v_cvt_pk_bf16_f32 v121, v122, v123
	v_cvt_pk_bf16_f32 v122, v124, v125
	v_cvt_pk_bf16_f32 v123, v126, v127
	v_add_f32_e32 v183, v183, v0
	s_nop 0
	s_waitcnt lgkmcnt(6)
	v_mfma_f32_32x32x16_bf16 v[80:95], v[212:215], v[120:123], v[80:95]
	s_waitcnt lgkmcnt(4)
	v_mfma_f32_32x32x16_bf16 v[64:79], v[216:219], v[120:123], v[64:79]
	s_waitcnt lgkmcnt(2)
	v_mfma_f32_32x32x16_bf16 v[48:63], v[220:223], v[120:123], v[48:63]
	s_waitcnt lgkmcnt(0)
	v_mfma_f32_32x32x16_bf16 v[32:47], v[224:227], v[120:123], v[32:47]
	s_cmp_lg_u32 s73, 0
	s_cbranch_scc1 .Lfa_o_bar
	s_waitcnt vmcnt(6)
	ds_write_b128 v197, v[144:147]
	ds_write_b128 v198, v[148:151] offset:17408
	s_waitcnt vmcnt(5)
	ds_write_b128 v197, v[152:155] offset:8704
	s_waitcnt vmcnt(4)
	ds_write_b128 v199, v[156:159] offset:17408
